# 6b/6d GEMM epilogue: row sum-of-squares of 15 rows reduced together with DPP row shifts and one b128 LDS read-modify-write per row group
# speedup vs baseline: 1.1053x; 1.0018x over previous
; DI void gemm_rownorm_residual(const Ctx& c, int m0, const bf16* A, int lda, int K, const bf16* Wt, const float* gpost,
;                               const float* xres, float* xdst, bf16* xbdst, bf16* lds, float* rowss, float* rstd_next) {
;     ...
;     const int lane = tid & 63, wave = tid >> 6, wm = wave >> 2, wn = wave & 3;
; #pragma unroll
;     for (int i = 0; i < 4; ++i)
; #pragma unroll
;       for (int r = 0; r < 4; ++r) {
;         const int row = wm * 64 + i * 16 + (lane >> 4) * 4 + r;
;         float ss = (acc[i][0][r] * acc[i][0][r] + acc[i][1][r] * acc[i][1][r]) + (acc[i][2][r] * acc[i][2][r] + acc[i][3][r] * acc[i][3][r]);
;         ss += __shfl_xor(ss, 1); ss += __shfl_xor(ss, 2); ss += __shfl_xor(ss, 4); ss += __shfl_xor(ss, 8);
;         if ((lane & 15) == 0) rowss[wn * 128 + row] += ss;
;       }
.LBB0_817:
	s_or_b64 exec, exec, s[0:1]
	s_waitcnt lgkmcnt(0)
	v_mov_b32_e32 v230, 0
	v_mul_f32_e32 v231, v55, v55
	v_fmac_f32_e32 v231, v51, v51
	v_fmac_f32_e32 v231, v35, v35
	v_fmac_f32_e32 v231, v43, v43
	v_mul_f32_e32 v232, v56, v56
	v_fmac_f32_e32 v232, v52, v52
	v_fmac_f32_e32 v232, v36, v36
	v_fmac_f32_e32 v232, v44, v44
	v_mul_f32_e32 v233, v57, v57
	v_fmac_f32_e32 v233, v53, v53
	v_fmac_f32_e32 v233, v37, v37
	v_fmac_f32_e32 v233, v45, v45
	v_mul_f32_e32 v234, v58, v58
	v_fmac_f32_e32 v234, v62, v62
	v_fmac_f32_e32 v234, v38, v38
	v_fmac_f32_e32 v234, v46, v46
	v_mul_f32_e32 v235, v59, v59
	v_fmac_f32_e32 v235, v63, v63
	v_fmac_f32_e32 v235, v39, v39
	v_fmac_f32_e32 v235, v47, v47
	v_mul_f32_e32 v236, v60, v60
	v_fmac_f32_e32 v236, v64, v64
	v_fmac_f32_e32 v236, v40, v40
	v_fmac_f32_e32 v236, v48, v48
	v_mul_f32_e32 v237, v61, v61
	v_fmac_f32_e32 v237, v65, v65
	v_fmac_f32_e32 v237, v41, v41
	v_fmac_f32_e32 v237, v49, v49
	v_mul_f32_e32 v238, v18, v18
	v_fmac_f32_e32 v238, v30, v30
	v_fmac_f32_e32 v238, v2, v2
	v_fmac_f32_e32 v238, v6, v6
	v_mul_f32_e32 v239, v19, v19
	v_fmac_f32_e32 v239, v31, v31
	v_fmac_f32_e32 v239, v3, v3
	v_fmac_f32_e32 v239, v7, v7
	v_mul_f32_e32 v240, v20, v20
	v_fmac_f32_e32 v240, v32, v32
	v_fmac_f32_e32 v240, v4, v4
	v_fmac_f32_e32 v240, v8, v8
	v_mul_f32_e32 v241, v21, v21
	v_fmac_f32_e32 v241, v33, v33
	v_fmac_f32_e32 v241, v5, v5
	v_fmac_f32_e32 v241, v9, v9
	v_mul_f32_e32 v242, v22, v22
	v_fmac_f32_e32 v242, v26, v26
	v_fmac_f32_e32 v242, v10, v10
	v_fmac_f32_e32 v242, v14, v14
	v_mul_f32_e32 v243, v23, v23
	v_fmac_f32_e32 v243, v27, v27
	v_fmac_f32_e32 v243, v11, v11
	v_fmac_f32_e32 v243, v15, v15
	v_mul_f32_e32 v244, v24, v24
	v_fmac_f32_e32 v244, v28, v28
	v_fmac_f32_e32 v244, v12, v12
	v_fmac_f32_e32 v244, v16, v16
	v_mul_f32_e32 v245, v25, v25
	v_fmac_f32_e32 v245, v29, v29
	v_fmac_f32_e32 v245, v13, v13
	v_fmac_f32_e32 v245, v17, v17
	v_add_f32_dpp v231, v231, v231 row_shl:8 row_mask:0xf bank_mask:0xf bound_ctrl:1
	v_add_f32_dpp v232, v232, v232 row_shl:8 row_mask:0xf bank_mask:0xf bound_ctrl:1
	v_add_f32_dpp v233, v233, v233 row_shl:8 row_mask:0xf bank_mask:0xf bound_ctrl:1
	v_add_f32_dpp v234, v234, v234 row_shl:8 row_mask:0xf bank_mask:0xf bound_ctrl:1
	v_add_f32_dpp v235, v235, v235 row_shl:8 row_mask:0xf bank_mask:0xf bound_ctrl:1
	v_add_f32_dpp v236, v236, v236 row_shl:8 row_mask:0xf bank_mask:0xf bound_ctrl:1
	v_add_f32_dpp v237, v237, v237 row_shl:8 row_mask:0xf bank_mask:0xf bound_ctrl:1
	v_add_f32_dpp v238, v238, v238 row_shl:8 row_mask:0xf bank_mask:0xf bound_ctrl:1
	v_add_f32_dpp v239, v239, v239 row_shl:8 row_mask:0xf bank_mask:0xf bound_ctrl:1
	v_add_f32_dpp v240, v240, v240 row_shl:8 row_mask:0xf bank_mask:0xf bound_ctrl:1
	v_add_f32_dpp v241, v241, v241 row_shl:8 row_mask:0xf bank_mask:0xf bound_ctrl:1
	v_add_f32_dpp v242, v242, v242 row_shl:8 row_mask:0xf bank_mask:0xf bound_ctrl:1
	v_add_f32_dpp v243, v243, v243 row_shl:8 row_mask:0xf bank_mask:0xf bound_ctrl:1
	v_add_f32_dpp v244, v244, v244 row_shl:8 row_mask:0xf bank_mask:0xf bound_ctrl:1
	v_add_f32_dpp v245, v245, v245 row_shl:8 row_mask:0xf bank_mask:0xf bound_ctrl:1
	v_add_f32_dpp v231, v231, v231 row_shl:4 row_mask:0xf bank_mask:0xf bound_ctrl:1
	v_add_f32_dpp v232, v232, v232 row_shl:4 row_mask:0xf bank_mask:0xf bound_ctrl:1
	v_add_f32_dpp v233, v233, v233 row_shl:4 row_mask:0xf bank_mask:0xf bound_ctrl:1
	v_add_f32_dpp v234, v234, v234 row_shl:4 row_mask:0xf bank_mask:0xf bound_ctrl:1
	v_add_f32_dpp v235, v235, v235 row_shl:4 row_mask:0xf bank_mask:0xf bound_ctrl:1
	v_add_f32_dpp v236, v236, v236 row_shl:4 row_mask:0xf bank_mask:0xf bound_ctrl:1
	v_add_f32_dpp v237, v237, v237 row_shl:4 row_mask:0xf bank_mask:0xf bound_ctrl:1
	v_add_f32_dpp v238, v238, v238 row_shl:4 row_mask:0xf bank_mask:0xf bound_ctrl:1
	v_add_f32_dpp v239, v239, v239 row_shl:4 row_mask:0xf bank_mask:0xf bound_ctrl:1
	v_add_f32_dpp v240, v240, v240 row_shl:4 row_mask:0xf bank_mask:0xf bound_ctrl:1
	v_add_f32_dpp v241, v241, v241 row_shl:4 row_mask:0xf bank_mask:0xf bound_ctrl:1
	v_add_f32_dpp v242, v242, v242 row_shl:4 row_mask:0xf bank_mask:0xf bound_ctrl:1
	v_add_f32_dpp v243, v243, v243 row_shl:4 row_mask:0xf bank_mask:0xf bound_ctrl:1
	v_add_f32_dpp v244, v244, v244 row_shl:4 row_mask:0xf bank_mask:0xf bound_ctrl:1
	v_add_f32_dpp v245, v245, v245 row_shl:4 row_mask:0xf bank_mask:0xf bound_ctrl:1
	v_add_f32_dpp v231, v231, v231 row_shl:2 row_mask:0xf bank_mask:0xf bound_ctrl:1
	v_add_f32_dpp v232, v232, v232 row_shl:2 row_mask:0xf bank_mask:0xf bound_ctrl:1
	v_add_f32_dpp v233, v233, v233 row_shl:2 row_mask:0xf bank_mask:0xf bound_ctrl:1
	v_add_f32_dpp v234, v234, v234 row_shl:2 row_mask:0xf bank_mask:0xf bound_ctrl:1
	v_add_f32_dpp v235, v235, v235 row_shl:2 row_mask:0xf bank_mask:0xf bound_ctrl:1
	v_add_f32_dpp v236, v236, v236 row_shl:2 row_mask:0xf bank_mask:0xf bound_ctrl:1
	v_add_f32_dpp v237, v237, v237 row_shl:2 row_mask:0xf bank_mask:0xf bound_ctrl:1
	v_add_f32_dpp v238, v238, v238 row_shl:2 row_mask:0xf bank_mask:0xf bound_ctrl:1
	v_add_f32_dpp v239, v239, v239 row_shl:2 row_mask:0xf bank_mask:0xf bound_ctrl:1
	v_add_f32_dpp v240, v240, v240 row_shl:2 row_mask:0xf bank_mask:0xf bound_ctrl:1
	v_add_f32_dpp v241, v241, v241 row_shl:2 row_mask:0xf bank_mask:0xf bound_ctrl:1
	v_add_f32_dpp v242, v242, v242 row_shl:2 row_mask:0xf bank_mask:0xf bound_ctrl:1
	v_add_f32_dpp v243, v243, v243 row_shl:2 row_mask:0xf bank_mask:0xf bound_ctrl:1
	v_add_f32_dpp v244, v244, v244 row_shl:2 row_mask:0xf bank_mask:0xf bound_ctrl:1
	v_add_f32_dpp v245, v245, v245 row_shl:2 row_mask:0xf bank_mask:0xf bound_ctrl:1
	v_add_f32_dpp v231, v231, v231 row_shl:1 row_mask:0xf bank_mask:0xf bound_ctrl:1
	v_add_f32_dpp v232, v232, v232 row_shl:1 row_mask:0xf bank_mask:0xf bound_ctrl:1
	v_add_f32_dpp v233, v233, v233 row_shl:1 row_mask:0xf bank_mask:0xf bound_ctrl:1
	v_add_f32_dpp v234, v234, v234 row_shl:1 row_mask:0xf bank_mask:0xf bound_ctrl:1
	v_add_f32_dpp v235, v235, v235 row_shl:1 row_mask:0xf bank_mask:0xf bound_ctrl:1
	v_add_f32_dpp v236, v236, v236 row_shl:1 row_mask:0xf bank_mask:0xf bound_ctrl:1
	v_add_f32_dpp v237, v237, v237 row_shl:1 row_mask:0xf bank_mask:0xf bound_ctrl:1
	v_add_f32_dpp v238, v238, v238 row_shl:1 row_mask:0xf bank_mask:0xf bound_ctrl:1
	v_add_f32_dpp v239, v239, v239 row_shl:1 row_mask:0xf bank_mask:0xf bound_ctrl:1
	v_add_f32_dpp v240, v240, v240 row_shl:1 row_mask:0xf bank_mask:0xf bound_ctrl:1
	v_add_f32_dpp v241, v241, v241 row_shl:1 row_mask:0xf bank_mask:0xf bound_ctrl:1
	v_add_f32_dpp v242, v242, v242 row_shl:1 row_mask:0xf bank_mask:0xf bound_ctrl:1
	v_add_f32_dpp v243, v243, v243 row_shl:1 row_mask:0xf bank_mask:0xf bound_ctrl:1
	v_add_f32_dpp v244, v244, v244 row_shl:1 row_mask:0xf bank_mask:0xf bound_ctrl:1
	v_add_f32_dpp v245, v245, v245 row_shl:1 row_mask:0xf bank_mask:0xf bound_ctrl:1
	s_and_saveexec_b64 s[0:1], vcc
	ds_read_b128 v[246:249], v80
	ds_read_b128 v[250:253], v80 offset:64
	s_waitcnt lgkmcnt(0)
; template <int BN_OUT> DI void ct_put(bf16* lds, int row, int col, float v) { lds[row * (BN_OUT + 8) + col] = f2bf(v); }
; DI void gemm_rownorm_residual(const Ctx& c, int m0, const bf16* A, int lda, int K, const bf16* Wt, const float* gpost,
;                               const float* xres, float* xdst, bf16* xbdst, bf16* lds, float* rowss, float* rstd_next) {
;     ...
;         float ss = (acc[i][0][r] * acc[i][0][r] + acc[i][1][r] * acc[i][1][r]) + (acc[i][2][r] * acc[i][2][r] + acc[i][3][r] * acc[i][3][r]);
;         ss += __shfl_xor(ss, 1); ss += __shfl_xor(ss, 2); ss += __shfl_xor(ss, 4); ss += __shfl_xor(ss, 8);
;         if ((lane & 15) == 0) rowss[wn * 128 + row] += ss;
;       }
;     __syncthreads();
;     ACC2_FOREACH(2, 4, 4, ct_put<256>(lds, row, col, acc[i][j][r]);)
;     ct_flush<128, 256>(lds, YS + (size_t)m0 * 1024 + nt * 256, 1024);
	v_add_f32_e32 v246, v246, v230
	v_add_f32_e32 v247, v247, v231
	v_add_f32_e32 v248, v248, v232
	v_add_f32_e32 v249, v249, v233
	v_add_f32_e32 v250, v250, v234
	v_add_f32_e32 v251, v251, v235
	v_add_f32_e32 v252, v252, v236
	v_add_f32_e32 v253, v253, v237
	ds_write_b128 v80, v[246:249]
	ds_write_b128 v80, v[250:253] offset:64
	ds_read_b128 v[246:249], v80 offset:128
	ds_read_b128 v[250:253], v80 offset:192
	s_waitcnt lgkmcnt(0)
	v_add_f32_e32 v246, v246, v238
	v_add_f32_e32 v247, v247, v239
	v_add_f32_e32 v248, v248, v240
	v_add_f32_e32 v249, v249, v241
	v_add_f32_e32 v250, v250, v242
	v_add_f32_e32 v251, v251, v243
	v_add_f32_e32 v252, v252, v244
	v_add_f32_e32 v253, v253, v245
	ds_write_b128 v80, v[246:249] offset:128
	ds_write_b128 v80, v[250:253] offset:192
	s_or_b64 exec, exec, s[0:1]
	v_mov_b32_e32 v0, v186
	s_waitcnt lgkmcnt(0)
	v_mov_b32_e32 v66, v186
	s_waitcnt vmcnt(0)
	s_barrier
	v_cvt_pk_bf16_f32 v50, v50, s0
	v_ashrrev_i32_e32 v66, 6, v66
	v_lshrrev_b32_e32 v67, 30, v66
	v_add_u32_e32 v67, v66, v67
	v_ashrrev_i32_e32 v67, 2, v67
	v_mul_i32_i24_e32 v68, 4, v67
	v_sub_u32_e32 v66, v66, v68
	v_lshrrev_b32_e32 v68, 2, v0
	v_and_b32_e32 v68, 12, v68
	v_and_b32_e32 v0, 15, v0
	v_lshl_or_b32 v67, v67, 6, v68
	s_movk_i32 s0, 0x210
	v_lshlrev_b32_e32 v0, 1, v0
	v_mul_lo_u32 v67, v67, s0
	v_lshl_or_b32 v0, v66, 7, v0
	s_movk_i32 s0, 0x50
	v_add3_u32 v66, s0, v67, v0
	ds_write_b16 v66, v50
	v_cvt_pk_bf16_f32 v50, v51, s0
	ds_write_b16 v66, v50 offset:528
	v_cvt_pk_bf16_f32 v50, v52, s0
	ds_write_b16 v66, v50 offset:1056
	v_cvt_pk_bf16_f32 v50, v53, s0
	ds_write_b16 v66, v50 offset:1584
	v_cvt_pk_bf16_f32 v50, v54, s0
	v_add3_u32 v0, s0, v0, v67
	v_cvt_pk_bf16_f32 v42, v42, s0
	v_cvt_pk_bf16_f32 v34, v34, s0
	ds_write_b16 v0, v50 offset:32
	ds_write_b16 v0, v42 offset:64
	ds_write_b16 v0, v34 offset:96
	v_cvt_pk_bf16_f32 v0, v35, s0
	ds_write_b16 v66, v0 offset:624
	v_cvt_pk_bf16_f32 v0, v36, s0
	ds_write_b16 v66, v0 offset:1152
	v_cvt_pk_bf16_f32 v0, v37, s0
	ds_write_b16 v66, v0 offset:1680
	v_cvt_pk_bf16_f32 v0, v62, s0
	ds_write_b16 v66, v0 offset:8448
	v_cvt_pk_bf16_f32 v0, v63, s0
	ds_write_b16 v66, v0 offset:8976
	v_cvt_pk_bf16_f32 v0, v64, s0
	ds_write_b16 v66, v0 offset:9504
	v_cvt_pk_bf16_f32 v0, v65, s0
	ds_write_b16 v66, v0 offset:10032
	v_cvt_pk_bf16_f32 v0, v58, s0
	ds_write_b16 v66, v0 offset:8480
	v_cvt_pk_bf16_f32 v0, v59, s0
	ds_write_b16 v66, v0 offset:9008
	v_cvt_pk_bf16_f32 v0, v60, s0
	ds_write_b16 v66, v0 offset:9536
	v_cvt_pk_bf16_f32 v0, v61, s0
	ds_write_b16 v66, v0 offset:10064
	v_cvt_pk_bf16_f32 v0, v46, s0
	ds_write_b16 v66, v0 offset:8512
	v_cvt_pk_bf16_f32 v0, v47, s0
	ds_write_b16 v66, v0 offset:9040
	v_cvt_pk_bf16_f32 v0, v48, s0
	ds_write_b16 v66, v0 offset:9568
	v_cvt_pk_bf16_f32 v0, v49, s0
	ds_write_b16 v66, v0 offset:10096
	v_cvt_pk_bf16_f32 v0, v38, s0
	ds_write_b16 v66, v0 offset:8544
	v_cvt_pk_bf16_f32 v0, v39, s0
	ds_write_b16 v66, v0 offset:9072
	v_cvt_pk_bf16_f32 v0, v40, s0
	ds_write_b16 v66, v0 offset:9600
	v_cvt_pk_bf16_f32 v0, v41, s0
	ds_write_b16 v66, v0 offset:10128
	v_cvt_pk_bf16_f32 v0, v30, s0
	ds_write_b16 v66, v0 offset:16896
	v_cvt_pk_bf16_f32 v0, v31, s0
	ds_write_b16 v66, v0 offset:17424
	v_cvt_pk_bf16_f32 v0, v32, s0
	ds_write_b16 v66, v0 offset:17952
	v_cvt_pk_bf16_f32 v0, v33, s0
	ds_write_b16 v66, v0 offset:18480
	v_cvt_pk_bf16_f32 v0, v18, s0
	ds_write_b16 v66, v0 offset:16928
	v_cvt_pk_bf16_f32 v0, v19, s0
	ds_write_b16 v66, v0 offset:17456
	v_cvt_pk_bf16_f32 v0, v20, s0
	ds_write_b16 v66, v0 offset:17984
	v_cvt_pk_bf16_f32 v0, v21, s0
	ds_write_b16 v66, v0 offset:18512
	v_cvt_pk_bf16_f32 v0, v6, s0
	ds_write_b16 v66, v0 offset:16960
	v_cvt_pk_bf16_f32 v0, v7, s0
	ds_write_b16 v66, v0 offset:17488
	v_cvt_pk_bf16_f32 v0, v8, s0
	ds_write_b16 v66, v0 offset:18016
	v_cvt_pk_bf16_f32 v0, v9, s0
	ds_write_b16 v66, v0 offset:18544
	v_cvt_pk_bf16_f32 v0, v2, s0
	ds_write_b16 v66, v0 offset:16992
	v_cvt_pk_bf16_f32 v0, v3, s0
	ds_write_b16 v66, v0 offset:17520
	v_cvt_pk_bf16_f32 v0, v4, s0
	ds_write_b16 v66, v0 offset:18048
	v_cvt_pk_bf16_f32 v0, v5, s0
	ds_write_b16 v66, v0 offset:18576
	v_cvt_pk_bf16_f32 v0, v26, s0
	ds_write_b16 v66, v0 offset:25344
	v_cvt_pk_bf16_f32 v0, v27, s0
	ds_write_b16 v66, v0 offset:25872
	v_cvt_pk_bf16_f32 v0, v28, s0
	ds_write_b16 v66, v0 offset:26400
	v_cvt_pk_bf16_f32 v0, v29, s0
	ds_write_b16 v66, v0 offset:26928
	v_cvt_pk_bf16_f32 v0, v22, s0
	ds_write_b16 v66, v0 offset:25376
	v_cvt_pk_bf16_f32 v0, v23, s0
	ds_write_b16 v66, v0 offset:25904
	v_cvt_pk_bf16_f32 v0, v24, s0
	ds_write_b16 v66, v0 offset:26432
	v_cvt_pk_bf16_f32 v0, v25, s0
	ds_write_b16 v66, v0 offset:26960
	v_cvt_pk_bf16_f32 v0, v14, s0
	ds_write_b16 v66, v0 offset:25408
	v_cvt_pk_bf16_f32 v0, v15, s0
	ds_write_b16 v66, v0 offset:25936
	v_cvt_pk_bf16_f32 v0, v16, s0
	ds_write_b16 v66, v0 offset:26464
	v_cvt_pk_bf16_f32 v0, v17, s0
	ds_write_b16 v66, v0 offset:26992
	v_cvt_pk_bf16_f32 v0, v10, s0
	ds_write_b16 v66, v0 offset:25440
	v_cvt_pk_bf16_f32 v0, v11, s0
	v_cvt_pk_bf16_f32 v50, v55, s0
	v_cvt_pk_bf16_f32 v42, v43, s0
	ds_write_b16 v66, v0 offset:25968
	v_cvt_pk_bf16_f32 v0, v12, s0
	ds_write_b16 v66, v50 offset:560
	v_cvt_pk_bf16_f32 v50, v56, s0
	ds_write_b16 v66, v42 offset:592
	v_cvt_pk_bf16_f32 v42, v44, s0
	ds_write_b16 v66, v0 offset:26496
	v_cvt_pk_bf16_f32 v0, v13, s0
	ds_write_b16 v66, v50 offset:1088
	v_cvt_pk_bf16_f32 v50, v57, s0
	ds_write_b16 v66, v42 offset:1120
	v_cvt_pk_bf16_f32 v42, v45, s0
	ds_write_b16 v66, v0 offset:27024
	v_mov_b32_e32 v0, v186
	s_movk_i32 s0, 0x1000
	ds_write_b16 v66, v50 offset:1616
	ds_write_b16 v66, v42 offset:1648
	s_waitcnt lgkmcnt(0)
	s_barrier
	s_nop 0
	v_cmp_gt_i32_e64 s[0:1], s0, v0
	s_and_saveexec_b64 s[28:29], s[0:1]
	s_movk_i32 s11, 0xdff
	s_cbranch_execz .LBB0_812
	s_lshl_b32 s0, s10, 9
	s_add_u32 s30, s19, s0
	s_addc_u32 s31, s36, 0
	v_lshl_add_u32 v2, v0, 4, v190
	v_lshlrev_b32_e32 v3, 3, v0
	s_mov_b64 s[34:35], 0

; DI void gemm_rownorm_residual(const Ctx& c, int m0, const bf16* A, int lda, int K, const bf16* Wt, const float* gpost,
;                               const float* xres, float* xdst, bf16* xbdst, bf16* lds, float* rowss, float* rstd_next) {
;     ...
;     const int lane = tid & 63, wave = tid >> 6, wm = wave >> 2, wn = wave & 3;
; #pragma unroll
;     for (int i = 0; i < 4; ++i)
; #pragma unroll
;       for (int r = 0; r < 4; ++r) {
;         const int row = wm * 64 + i * 16 + (lane >> 4) * 4 + r;
;         float ss = (acc[i][0][r] * acc[i][0][r] + acc[i][1][r] * acc[i][1][r]) + (acc[i][2][r] * acc[i][2][r] + acc[i][3][r] * acc[i][3][r]);
;         ss += __shfl_xor(ss, 1); ss += __shfl_xor(ss, 2); ss += __shfl_xor(ss, 4); ss += __shfl_xor(ss, 8);
;         if ((lane & 15) == 0) rowss[wn * 128 + row] += ss;
;       }
.LBB0_865:
	s_or_b64 exec, exec, s[0:1]
	s_waitcnt lgkmcnt(0)
	v_mov_b32_e32 v230, 0
	v_mul_f32_e32 v231, v55, v55
	v_fmac_f32_e32 v231, v59, v59
	v_fmac_f32_e32 v231, v39, v39
	v_fmac_f32_e32 v231, v47, v47
	v_mul_f32_e32 v232, v56, v56
	v_fmac_f32_e32 v232, v60, v60
	v_fmac_f32_e32 v232, v40, v40
	v_fmac_f32_e32 v232, v48, v48
	v_mul_f32_e32 v233, v57, v57
	v_fmac_f32_e32 v233, v61, v61
	v_fmac_f32_e32 v233, v41, v41
	v_fmac_f32_e32 v233, v49, v49
	v_mul_f32_e32 v234, v50, v50
	v_fmac_f32_e32 v234, v62, v62
	v_fmac_f32_e32 v234, v34, v34
	v_fmac_f32_e32 v234, v42, v42
	v_mul_f32_e32 v235, v51, v51
	v_fmac_f32_e32 v235, v63, v63
	v_fmac_f32_e32 v235, v35, v35
	v_fmac_f32_e32 v235, v43, v43
	v_mul_f32_e32 v236, v52, v52
	v_fmac_f32_e32 v236, v64, v64
	v_fmac_f32_e32 v236, v36, v36
	v_fmac_f32_e32 v236, v44, v44
	v_mul_f32_e32 v237, v53, v53
	v_fmac_f32_e32 v237, v65, v65
	v_fmac_f32_e32 v237, v37, v37
	v_fmac_f32_e32 v237, v45, v45
	v_mul_f32_e32 v238, v18, v18
	v_fmac_f32_e32 v238, v30, v30
	v_fmac_f32_e32 v238, v2, v2
	v_fmac_f32_e32 v238, v6, v6
	v_mul_f32_e32 v239, v19, v19
	v_fmac_f32_e32 v239, v31, v31
	v_fmac_f32_e32 v239, v3, v3
	v_fmac_f32_e32 v239, v7, v7
	v_mul_f32_e32 v240, v20, v20
	v_fmac_f32_e32 v240, v32, v32
	v_fmac_f32_e32 v240, v4, v4
	v_fmac_f32_e32 v240, v8, v8
	v_mul_f32_e32 v241, v21, v21
	v_fmac_f32_e32 v241, v33, v33
	v_fmac_f32_e32 v241, v5, v5
	v_fmac_f32_e32 v241, v9, v9
	v_mul_f32_e32 v242, v22, v22
	v_fmac_f32_e32 v242, v26, v26
	v_fmac_f32_e32 v242, v10, v10
	v_fmac_f32_e32 v242, v14, v14
	v_mul_f32_e32 v243, v23, v23
	v_fmac_f32_e32 v243, v27, v27
	v_fmac_f32_e32 v243, v11, v11
	v_fmac_f32_e32 v243, v15, v15
	v_mul_f32_e32 v244, v24, v24
	v_fmac_f32_e32 v244, v28, v28
	v_fmac_f32_e32 v244, v12, v12
	v_fmac_f32_e32 v244, v16, v16
	v_mul_f32_e32 v245, v25, v25
	v_fmac_f32_e32 v245, v29, v29
	v_fmac_f32_e32 v245, v13, v13
	v_fmac_f32_e32 v245, v17, v17
	v_add_f32_dpp v231, v231, v231 row_shl:8 row_mask:0xf bank_mask:0xf bound_ctrl:1
	v_add_f32_dpp v232, v232, v232 row_shl:8 row_mask:0xf bank_mask:0xf bound_ctrl:1
	v_add_f32_dpp v233, v233, v233 row_shl:8 row_mask:0xf bank_mask:0xf bound_ctrl:1
	v_add_f32_dpp v234, v234, v234 row_shl:8 row_mask:0xf bank_mask:0xf bound_ctrl:1
	v_add_f32_dpp v235, v235, v235 row_shl:8 row_mask:0xf bank_mask:0xf bound_ctrl:1
	v_add_f32_dpp v236, v236, v236 row_shl:8 row_mask:0xf bank_mask:0xf bound_ctrl:1
	v_add_f32_dpp v237, v237, v237 row_shl:8 row_mask:0xf bank_mask:0xf bound_ctrl:1
	v_add_f32_dpp v238, v238, v238 row_shl:8 row_mask:0xf bank_mask:0xf bound_ctrl:1
	v_add_f32_dpp v239, v239, v239 row_shl:8 row_mask:0xf bank_mask:0xf bound_ctrl:1
	v_add_f32_dpp v240, v240, v240 row_shl:8 row_mask:0xf bank_mask:0xf bound_ctrl:1
	v_add_f32_dpp v241, v241, v241 row_shl:8 row_mask:0xf bank_mask:0xf bound_ctrl:1
	v_add_f32_dpp v242, v242, v242 row_shl:8 row_mask:0xf bank_mask:0xf bound_ctrl:1
	v_add_f32_dpp v243, v243, v243 row_shl:8 row_mask:0xf bank_mask:0xf bound_ctrl:1
	v_add_f32_dpp v244, v244, v244 row_shl:8 row_mask:0xf bank_mask:0xf bound_ctrl:1
	v_add_f32_dpp v245, v245, v245 row_shl:8 row_mask:0xf bank_mask:0xf bound_ctrl:1
	v_add_f32_dpp v231, v231, v231 row_shl:4 row_mask:0xf bank_mask:0xf bound_ctrl:1
	v_add_f32_dpp v232, v232, v232 row_shl:4 row_mask:0xf bank_mask:0xf bound_ctrl:1
	v_add_f32_dpp v233, v233, v233 row_shl:4 row_mask:0xf bank_mask:0xf bound_ctrl:1
	v_add_f32_dpp v234, v234, v234 row_shl:4 row_mask:0xf bank_mask:0xf bound_ctrl:1
	v_add_f32_dpp v235, v235, v235 row_shl:4 row_mask:0xf bank_mask:0xf bound_ctrl:1
	v_add_f32_dpp v236, v236, v236 row_shl:4 row_mask:0xf bank_mask:0xf bound_ctrl:1
	v_add_f32_dpp v237, v237, v237 row_shl:4 row_mask:0xf bank_mask:0xf bound_ctrl:1
	v_add_f32_dpp v238, v238, v238 row_shl:4 row_mask:0xf bank_mask:0xf bound_ctrl:1
	v_add_f32_dpp v239, v239, v239 row_shl:4 row_mask:0xf bank_mask:0xf bound_ctrl:1
	v_add_f32_dpp v240, v240, v240 row_shl:4 row_mask:0xf bank_mask:0xf bound_ctrl:1
	v_add_f32_dpp v241, v241, v241 row_shl:4 row_mask:0xf bank_mask:0xf bound_ctrl:1
	v_add_f32_dpp v242, v242, v242 row_shl:4 row_mask:0xf bank_mask:0xf bound_ctrl:1
	v_add_f32_dpp v243, v243, v243 row_shl:4 row_mask:0xf bank_mask:0xf bound_ctrl:1
	v_add_f32_dpp v244, v244, v244 row_shl:4 row_mask:0xf bank_mask:0xf bound_ctrl:1
	v_add_f32_dpp v245, v245, v245 row_shl:4 row_mask:0xf bank_mask:0xf bound_ctrl:1
	v_add_f32_dpp v231, v231, v231 row_shl:2 row_mask:0xf bank_mask:0xf bound_ctrl:1
	v_add_f32_dpp v232, v232, v232 row_shl:2 row_mask:0xf bank_mask:0xf bound_ctrl:1
	v_add_f32_dpp v233, v233, v233 row_shl:2 row_mask:0xf bank_mask:0xf bound_ctrl:1
	v_add_f32_dpp v234, v234, v234 row_shl:2 row_mask:0xf bank_mask:0xf bound_ctrl:1
	v_add_f32_dpp v235, v235, v235 row_shl:2 row_mask:0xf bank_mask:0xf bound_ctrl:1
	v_add_f32_dpp v236, v236, v236 row_shl:2 row_mask:0xf bank_mask:0xf bound_ctrl:1
	v_add_f32_dpp v237, v237, v237 row_shl:2 row_mask:0xf bank_mask:0xf bound_ctrl:1
	v_add_f32_dpp v238, v238, v238 row_shl:2 row_mask:0xf bank_mask:0xf bound_ctrl:1
	v_add_f32_dpp v239, v239, v239 row_shl:2 row_mask:0xf bank_mask:0xf bound_ctrl:1
	v_add_f32_dpp v240, v240, v240 row_shl:2 row_mask:0xf bank_mask:0xf bound_ctrl:1
	v_add_f32_dpp v241, v241, v241 row_shl:2 row_mask:0xf bank_mask:0xf bound_ctrl:1
	v_add_f32_dpp v242, v242, v242 row_shl:2 row_mask:0xf bank_mask:0xf bound_ctrl:1
	v_add_f32_dpp v243, v243, v243 row_shl:2 row_mask:0xf bank_mask:0xf bound_ctrl:1
	v_add_f32_dpp v244, v244, v244 row_shl:2 row_mask:0xf bank_mask:0xf bound_ctrl:1
	v_add_f32_dpp v245, v245, v245 row_shl:2 row_mask:0xf bank_mask:0xf bound_ctrl:1
	v_add_f32_dpp v231, v231, v231 row_shl:1 row_mask:0xf bank_mask:0xf bound_ctrl:1
	v_add_f32_dpp v232, v232, v232 row_shl:1 row_mask:0xf bank_mask:0xf bound_ctrl:1
	v_add_f32_dpp v233, v233, v233 row_shl:1 row_mask:0xf bank_mask:0xf bound_ctrl:1
	v_add_f32_dpp v234, v234, v234 row_shl:1 row_mask:0xf bank_mask:0xf bound_ctrl:1
	v_add_f32_dpp v235, v235, v235 row_shl:1 row_mask:0xf bank_mask:0xf bound_ctrl:1
	v_add_f32_dpp v236, v236, v236 row_shl:1 row_mask:0xf bank_mask:0xf bound_ctrl:1
	v_add_f32_dpp v237, v237, v237 row_shl:1 row_mask:0xf bank_mask:0xf bound_ctrl:1
	v_add_f32_dpp v238, v238, v238 row_shl:1 row_mask:0xf bank_mask:0xf bound_ctrl:1
	v_add_f32_dpp v239, v239, v239 row_shl:1 row_mask:0xf bank_mask:0xf bound_ctrl:1
	v_add_f32_dpp v240, v240, v240 row_shl:1 row_mask:0xf bank_mask:0xf bound_ctrl:1
	v_add_f32_dpp v241, v241, v241 row_shl:1 row_mask:0xf bank_mask:0xf bound_ctrl:1
	v_add_f32_dpp v242, v242, v242 row_shl:1 row_mask:0xf bank_mask:0xf bound_ctrl:1
	v_add_f32_dpp v243, v243, v243 row_shl:1 row_mask:0xf bank_mask:0xf bound_ctrl:1
	v_add_f32_dpp v244, v244, v244 row_shl:1 row_mask:0xf bank_mask:0xf bound_ctrl:1
	v_add_f32_dpp v245, v245, v245 row_shl:1 row_mask:0xf bank_mask:0xf bound_ctrl:1
	s_and_saveexec_b64 s[0:1], vcc
	ds_read_b128 v[246:249], v80
	ds_read_b128 v[250:253], v80 offset:64
	s_waitcnt lgkmcnt(0)
; template <int BN_OUT> DI void ct_put(bf16* lds, int row, int col, float v) { lds[row * (BN_OUT + 8) + col] = f2bf(v); }
; DI void gemm_rownorm_residual(const Ctx& c, int m0, const bf16* A, int lda, int K, const bf16* Wt, const float* gpost,
;                               const float* xres, float* xdst, bf16* xbdst, bf16* lds, float* rowss, float* rstd_next) {
;     ...
;         float ss = (acc[i][0][r] * acc[i][0][r] + acc[i][1][r] * acc[i][1][r]) + (acc[i][2][r] * acc[i][2][r] + acc[i][3][r] * acc[i][3][r]);
;         ss += __shfl_xor(ss, 1); ss += __shfl_xor(ss, 2); ss += __shfl_xor(ss, 4); ss += __shfl_xor(ss, 8);
;         if ((lane & 15) == 0) rowss[wn * 128 + row] += ss;
;       }
;     __syncthreads();
;     ACC2_FOREACH(2, 4, 4, ct_put<256>(lds, row, col, acc[i][j][r]);)
;     ct_flush<128, 256>(lds, YS + (size_t)m0 * 1024 + nt * 256, 1024);
	v_add_f32_e32 v246, v246, v230
	v_add_f32_e32 v247, v247, v231
	v_add_f32_e32 v248, v248, v232
	v_add_f32_e32 v249, v249, v233
	v_add_f32_e32 v250, v250, v234
	v_add_f32_e32 v251, v251, v235
	v_add_f32_e32 v252, v252, v236
	v_add_f32_e32 v253, v253, v237
	ds_write_b128 v80, v[246:249]
	ds_write_b128 v80, v[250:253] offset:64
	ds_read_b128 v[246:249], v80 offset:128
	ds_read_b128 v[250:253], v80 offset:192
	s_waitcnt lgkmcnt(0)
	v_add_f32_e32 v246, v246, v238
	v_add_f32_e32 v247, v247, v239
	v_add_f32_e32 v248, v248, v240
	v_add_f32_e32 v249, v249, v241
	v_add_f32_e32 v250, v250, v242
	v_add_f32_e32 v251, v251, v243
	v_add_f32_e32 v252, v252, v244
	v_add_f32_e32 v253, v253, v245
	ds_write_b128 v80, v[246:249] offset:128
	ds_write_b128 v80, v[250:253] offset:192
	s_or_b64 exec, exec, s[0:1]
	v_mov_b32_e32 v0, v186
	s_waitcnt lgkmcnt(0)
	v_mov_b32_e32 v66, v186
	s_waitcnt vmcnt(0)
	s_barrier
	v_cvt_pk_bf16_f32 v58, v58, s0
	v_ashrrev_i32_e32 v66, 6, v66
	v_lshrrev_b32_e32 v67, 30, v66
	v_add_u32_e32 v67, v66, v67
	v_ashrrev_i32_e32 v67, 2, v67
	v_mul_i32_i24_e32 v68, 4, v67
	v_sub_u32_e32 v66, v66, v68
	v_lshrrev_b32_e32 v68, 2, v0
	v_and_b32_e32 v68, 12, v68
	v_and_b32_e32 v0, 15, v0
	v_lshl_or_b32 v67, v67, 6, v68
	s_movk_i32 s0, 0x210
	v_lshlrev_b32_e32 v0, 1, v0
	v_mul_lo_u32 v67, v67, s0
	v_lshl_or_b32 v0, v66, 7, v0
	s_movk_i32 s0, 0x50
	v_add3_u32 v66, s0, v67, v0
	v_cvt_pk_bf16_f32 v54, v54, s0
	v_add3_u32 v0, s0, v0, v67
	v_cvt_pk_bf16_f32 v46, v46, s0
	v_cvt_pk_bf16_f32 v38, v38, s0
	ds_write_b16 v0, v54 offset:32
	ds_write_b16 v0, v46 offset:64
	ds_write_b16 v0, v38 offset:96
	v_cvt_pk_bf16_f32 v0, v39, s0
	ds_write_b16 v66, v0 offset:624
	v_cvt_pk_bf16_f32 v0, v40, s0
	ds_write_b16 v66, v0 offset:1152
	v_cvt_pk_bf16_f32 v0, v41, s0
	ds_write_b16 v66, v0 offset:1680
	v_cvt_pk_bf16_f32 v0, v62, s0
	ds_write_b16 v66, v0 offset:8448
	v_cvt_pk_bf16_f32 v0, v63, s0
	ds_write_b16 v66, v0 offset:8976
	v_cvt_pk_bf16_f32 v0, v64, s0
	ds_write_b16 v66, v0 offset:9504
	v_cvt_pk_bf16_f32 v0, v65, s0
	ds_write_b16 v66, v0 offset:10032
	v_cvt_pk_bf16_f32 v0, v50, s0
	ds_write_b16 v66, v0 offset:8480
	v_cvt_pk_bf16_f32 v0, v51, s0
	ds_write_b16 v66, v0 offset:9008
	v_cvt_pk_bf16_f32 v0, v52, s0
	ds_write_b16 v66, v0 offset:9536
	v_cvt_pk_bf16_f32 v0, v53, s0
	ds_write_b16 v66, v0 offset:10064
	v_cvt_pk_bf16_f32 v0, v42, s0
	ds_write_b16 v66, v0 offset:8512
	v_cvt_pk_bf16_f32 v0, v43, s0
	ds_write_b16 v66, v0 offset:9040
	v_cvt_pk_bf16_f32 v0, v44, s0
	ds_write_b16 v66, v0 offset:9568
	v_cvt_pk_bf16_f32 v0, v45, s0
	ds_write_b16 v66, v0 offset:10096
	v_cvt_pk_bf16_f32 v0, v34, s0
	ds_write_b16 v66, v0 offset:8544
	v_cvt_pk_bf16_f32 v0, v35, s0
	ds_write_b16 v66, v0 offset:9072
	v_cvt_pk_bf16_f32 v0, v36, s0
	ds_write_b16 v66, v0 offset:9600
	v_cvt_pk_bf16_f32 v0, v37, s0
	ds_write_b16 v66, v0 offset:10128
	v_cvt_pk_bf16_f32 v0, v30, s0
	ds_write_b16 v66, v0 offset:16896
	v_cvt_pk_bf16_f32 v0, v31, s0
	ds_write_b16 v66, v0 offset:17424
	v_cvt_pk_bf16_f32 v0, v32, s0
	ds_write_b16 v66, v0 offset:17952
	v_cvt_pk_bf16_f32 v0, v33, s0
	ds_write_b16 v66, v0 offset:18480
	v_cvt_pk_bf16_f32 v0, v18, s0
	ds_write_b16 v66, v0 offset:16928
	v_cvt_pk_bf16_f32 v0, v19, s0
	ds_write_b16 v66, v0 offset:17456
	v_cvt_pk_bf16_f32 v0, v20, s0
	ds_write_b16 v66, v0 offset:17984
	v_cvt_pk_bf16_f32 v0, v21, s0
	ds_write_b16 v66, v0 offset:18512
	v_cvt_pk_bf16_f32 v0, v6, s0
	ds_write_b16 v66, v0 offset:16960
	v_cvt_pk_bf16_f32 v0, v7, s0
	ds_write_b16 v66, v0 offset:17488
	v_cvt_pk_bf16_f32 v0, v8, s0
	ds_write_b16 v66, v0 offset:18016
	v_cvt_pk_bf16_f32 v0, v9, s0
	ds_write_b16 v66, v0 offset:18544
	v_cvt_pk_bf16_f32 v0, v2, s0
	ds_write_b16 v66, v0 offset:16992
	v_cvt_pk_bf16_f32 v0, v3, s0
	ds_write_b16 v66, v0 offset:17520
	v_cvt_pk_bf16_f32 v0, v4, s0
	ds_write_b16 v66, v0 offset:18048
	v_cvt_pk_bf16_f32 v0, v5, s0
	ds_write_b16 v66, v0 offset:18576
	v_cvt_pk_bf16_f32 v0, v26, s0
	ds_write_b16 v66, v0 offset:25344
	v_cvt_pk_bf16_f32 v0, v27, s0
	ds_write_b16 v66, v0 offset:25872
	v_cvt_pk_bf16_f32 v0, v28, s0
	ds_write_b16 v66, v0 offset:26400
	v_cvt_pk_bf16_f32 v0, v29, s0
	ds_write_b16 v66, v0 offset:26928
	v_cvt_pk_bf16_f32 v0, v22, s0
	ds_write_b16 v66, v0 offset:25376
	v_cvt_pk_bf16_f32 v0, v23, s0
	ds_write_b16 v66, v0 offset:25904
	v_cvt_pk_bf16_f32 v0, v24, s0
	ds_write_b16 v66, v0 offset:26432
	v_cvt_pk_bf16_f32 v0, v25, s0
	ds_write_b16 v66, v0 offset:26960
	v_cvt_pk_bf16_f32 v0, v14, s0
	ds_write_b16 v66, v0 offset:25408
	v_cvt_pk_bf16_f32 v0, v15, s0
	ds_write_b16 v66, v0 offset:25936
	v_cvt_pk_bf16_f32 v0, v16, s0
	ds_write_b16 v66, v0 offset:26464
	v_cvt_pk_bf16_f32 v0, v17, s0
	ds_write_b16 v66, v0 offset:26992
	v_cvt_pk_bf16_f32 v0, v10, s0
	ds_write_b16 v66, v0 offset:25440
	v_cvt_pk_bf16_f32 v0, v11, s0
	ds_write_b16 v66, v58
	v_cvt_pk_bf16_f32 v58, v59, s0
	v_cvt_pk_bf16_f32 v54, v55, s0
	v_cvt_pk_bf16_f32 v46, v47, s0
	ds_write_b16 v66, v0 offset:25968
	v_cvt_pk_bf16_f32 v0, v12, s0
	ds_write_b16 v66, v58 offset:528
	v_cvt_pk_bf16_f32 v58, v60, s0
	ds_write_b16 v66, v54 offset:560
	v_cvt_pk_bf16_f32 v54, v56, s0
	ds_write_b16 v66, v46 offset:592
	v_cvt_pk_bf16_f32 v46, v48, s0
	ds_write_b16 v66, v0 offset:26496
	v_cvt_pk_bf16_f32 v0, v13, s0
	ds_write_b16 v66, v58 offset:1056
	v_cvt_pk_bf16_f32 v58, v61, s0
	ds_write_b16 v66, v54 offset:1088
	v_cvt_pk_bf16_f32 v54, v57, s0
	ds_write_b16 v66, v46 offset:1120
	v_cvt_pk_bf16_f32 v46, v49, s0
	ds_write_b16 v66, v0 offset:27024
	v_mov_b32_e32 v0, v186
	s_movk_i32 s0, 0x1000
	ds_write_b16 v66, v58 offset:1584
	ds_write_b16 v66, v54 offset:1616
	ds_write_b16 v66, v46 offset:1648
	s_waitcnt lgkmcnt(0)
	s_barrier
	s_nop 0
	v_cmp_gt_i32_e64 s[0:1], s0, v0
	s_and_saveexec_b64 s[28:29], s[0:1]
	s_movk_i32 s11, 0xdff
	s_cbranch_execz .LBB0_860
	s_lshl_b32 s0, s10, 9
	s_add_u32 s30, s19, s0
	s_addc_u32 s31, s36, 0
	v_lshl_add_u32 v2, v0, 4, v190
	v_lshlrev_b32_e32 v3, 3, v0
	s_mov_b64 s[34:35], 0
